# RET chunk loop: L2 prefetch of chunk c+2 K/Q/V lines (one dword per 128B line), kept in flight across one chunk
# speedup vs baseline: 1.0077x; 1.0077x over previous
; #define LAS __attribute__((address_space(3)))
; __device__ __forceinline__ void unpack8(const v4u w, float (&f)[8]) { f[0] = bf_lo(w.x); f[1] = bf_hi(w.x); f[2] = bf_lo(w.y); f[3] = bf_hi(w.y); f[4] = bf_lo(w.z); f[5] = bf_hi(w.z); f[6] = bf_lo(w.w); f[7] = bf_hi(w.w); }
; #define RT_LOAD_Q(cc) do { int ll_ = lane; asm volatile("" : "+v"(ll_)); const int t_ = 128 * (cc) - 112 + i0 + (ll_ & 15); \
;             _Pragma("unroll") for (int s = 0; s < 8; ++s) Qf[s] = t_ >= 0 ? *(const bf16x8*)(Qg + (size_t)(b * TP + t_) * 2048 + 32 * s + 8 * (ll_ >> 4)) : (bf16x8){0, 0, 0, 0, 0, 0, 0, 0}; } while (0)
; __device__ __forceinline__ void ph_ret_fast(const Params& p, int jl, LAS unsigned char* lds, int tid, int lane, int wave) {
;     ...
;         const float gamma = 1.0f - exp2f(-5.0f - (float)h), lg = log2f(gamma), g128 = exp2f(128.f * lg), g127 = exp2f(127.f * lg);
;         const int it_ = wave < 4 ? wave : 11 - wave, i0 = 16 * it_, d0 = 32 * wave;
;         f32x4 Sacc[2][4];
; #pragma unroll
;         for (int a = 0; a < 2; ++a)
; #pragma unroll
;             for (int c = 0; c < 4; ++c) Sacc[a][c] = (f32x4){0.f, 0.f, 0.f, 0.f};
;         __syncthreads();
;         for (int i = tid; i < 64 * RT_SP / 16; i += NTHR) *(LAS v4u*)(lds + RT_ST_OFF + i * 16) = (v4u){0u, 0u, 0u, 0u};
;         v4u kst[8], vst[2];
;         const bf16* Kg = QK + 1024 + 256 * h; const bf16* Vg = V + 512 * h + 64 * es; const bf16* Qg = QK + 256 * h;
;     ...
;         RT_LOAD_STAGE(0);
;         bf16x8 Qf[8];
;     ...
;         RT_LOAD_Q(0);
;         for (int c = 0; c < 17; ++c) {
;             __syncthreads();
; #pragma unroll
;             for (int k_ = 0; k_ < 8; ++k_) { const int id_ = tid + 512 * k_, row_ = id_ >> 5, ch_ = id_ & 31; *(LAS v4u*)(lds + RT_K_OFF + row_ * RT_KP + ch_ * 16) = kst[k_]; }
; #pragma unroll
;             for (int k_ = 0; k_ < 2; ++k_) { const int id_ = tid + 512 * k_, row_ = id_ >> 3, ch_ = id_ & 7;
;                 float f[8]; unpack8(vst[k_], f); const float sc = exp2f(-(float)row_ * lg);
; #pragma unroll
;                 for (int e = 0; e < 8; ++e) f[e] *= sc;
.LBB0_383:
	s_lshl_b32 s0, s12, 1
	v_readlane_b32 s12, v252, 54
	v_readlane_b32 s13, v252, 55
	s_add_u32 s0, s12, s0
	s_addc_u32 s1, s13, 0
	s_add_u32 s0, s0, s76
	v_mul_f32_e32 v0, v76, v164
	s_mov_b32 s76, 0xc2fc0000
	v_cmp_gt_f32_e32 vcc, s76, v0
	v_div_scale_f32 v75, s[12:13], v118, v118, v77
	s_nop 0
	v_cndmask_b32_e32 v74, 0, v227, vcc
	v_fmac_f32_e32 v74, v76, v164
	v_exp_f32_e32 v74, v74
	v_rcp_f32_e32 v78, v75
	v_cndmask_b32_e32 v0, 0, v228, vcc
	s_addc_u32 s1, s1, 0
	v_ldexp_f32 v117, v74, v0
	v_fma_f32 v0, -v75, v78, 1.0
	v_fmac_f32_e32 v78, v0, v78
	v_div_scale_f32 v0, vcc, v77, v118, v77
	v_mul_f32_e32 v74, v0, v78
	v_fma_f32 v79, -v75, v74, v0
	v_fmac_f32_e32 v74, v79, v78
	v_fma_f32 v0, -v75, v74, v0
	v_div_fmas_f32 v0, v0, v78, v74
	v_div_fixup_f32 v122, v0, v118, v77
	v_mul_f32_e64 v0, v76, -v166
	v_cmp_gt_f32_e32 vcc, s76, v0
	v_mul_f32_e64 v75, v76, -v167
	v_mov_b32_e32 v115, v1
	v_cndmask_b32_e32 v0, 0, v228, vcc
	v_cndmask_b32_e32 v74, 0, v227, vcc
	v_cmp_gt_f32_e32 vcc, s76, v75
	v_fma_f32 v74, v76, -v166, v74
	v_exp_f32_e32 v74, v74
	v_cndmask_b32_e32 v77, 0, v227, vcc
	v_fma_f32 v77, v76, -v167, v77
	v_exp_f32_e32 v77, v77
	v_cndmask_b32_e32 v75, 0, v228, vcc
	v_ldexp_f32 v205, v74, v0
	v_mul_f32_e32 v0, v76, v170
	v_lshl_add_u64 v[126:127], s[0:1], 0, v[114:115]
	v_ldexp_f32 v115, v77, v75
	v_cmp_gt_f32_e32 vcc, s76, v0
	v_mul_f32_e32 v75, v76, v171
	v_mul_f32_e32 v78, v76, v172
	v_cndmask_b32_e32 v0, 0, v228, vcc
	v_cndmask_b32_e32 v74, 0, v227, vcc
	v_cmp_gt_f32_e32 vcc, s76, v75
	v_mul_f32_e32 v80, v76, v173
	v_fmac_f32_e32 v74, v76, v170
	v_cndmask_b32_e32 v75, 0, v228, vcc
	v_cndmask_b32_e32 v77, 0, v227, vcc
	v_cmp_gt_f32_e32 vcc, s76, v78
	v_fmac_f32_e32 v77, v76, v171
	v_exp_f32_e32 v74, v74
	v_cndmask_b32_e32 v78, 0, v228, vcc
	v_cndmask_b32_e32 v79, 0, v227, vcc
	v_cmp_gt_f32_e32 vcc, s76, v80
	v_fmac_f32_e32 v79, v76, v172
	v_exp_f32_e32 v77, v77
	v_cndmask_b32_e32 v81, 0, v227, vcc
	v_fmac_f32_e32 v81, v76, v173
	v_exp_f32_e32 v79, v79
	v_exp_f32_e32 v76, v81
	v_cndmask_b32_e32 v80, 0, v228, vcc
	v_mov_b32_e32 v124, v122
	v_mov_b32_e32 v125, v122
	v_mov_b32_e32 v120, v118
	v_mov_b32_e32 v121, v118
	v_ldexp_f32 v130, v74, v0
	v_ldexp_f32 v131, v77, v75
	v_ldexp_f32 v134, v79, v78
	v_ldexp_f32 v135, v76, v80
	v_add_u32_e32 v206, s94, v185
	s_add_i32 s12, s14, s94
	v_mov_b32_e32 v129, v128
	v_mov_b32_e32 v132, v128
	v_mov_b32_e32 v133, v128
	v_mov_b32_e32 v136, v128
	v_mov_b32_e32 v137, v128
	v_mov_b32_e32 v138, v128
	v_mov_b32_e32 v139, v128
	v_mov_b32_e32 v140, v128
	v_mov_b32_e32 v141, v128
	v_mov_b32_e32 v142, v128
	v_mov_b32_e32 v143, v128
	v_mov_b32_e32 v144, v128
	v_mov_b32_e32 v145, v128
	v_mov_b32_e32 v146, v128
	v_mov_b32_e32 v147, v128
	v_mov_b32_e32 v152, v128
	v_mov_b32_e32 v153, v128
	v_mov_b32_e32 v158, v128
	v_mov_b32_e32 v159, v128
	v_mov_b32_e32 v148, v128
	v_mov_b32_e32 v149, v128
	v_mov_b32_e32 v150, v128
	v_mov_b32_e32 v151, v128
	v_mov_b32_e32 v154, v128
	v_mov_b32_e32 v155, v128
	v_mov_b32_e32 v156, v128
	v_mov_b32_e32 v157, v128
	v_mov_b32_e32 v160, v128
	v_mov_b32_e32 v161, v128
	v_mov_b32_e32 v162, v128
	v_mov_b32_e32 v163, v128
	s_add_i32 s101, s94, 16
	s_lshl_b32 s101, s101, 12
	v_and_b32_e32 v239, 3, v194
	v_lshlrev_b32_e32 v239, 7, v239
	v_lshl_or_b32 v239, v194, 10, v239
	v_and_b32_e32 v239, 0x7f180, v239
	v_add_u32_e32 v239, s101, v239
	global_load_dword v223, v239, s[86:87]
	global_load_dword v223, v239, s[90:91]
	s_nop 1
	v_and_b32_e32 v239, 3, v194
	v_lshlrev_b32_e32 v239, 5, v239
	v_lshl_or_b32 v239, v194, 10, v239
	v_and_b32_e32 v239, 0x7f060, v239
	v_add_u32_e32 v239, s101, v239
	global_load_dword v223, v239, s[88:89]
	s_waitcnt vmcnt(0)
	s_branch .LBB0_386

; #define LAS __attribute__((address_space(3)))
; __device__ __forceinline__ void unpack8(const v4u w, float (&f)[8]) { f[0] = bf_lo(w.x); f[1] = bf_hi(w.x); f[2] = bf_lo(w.y); f[3] = bf_hi(w.y); f[4] = bf_lo(w.z); f[5] = bf_hi(w.z); f[6] = bf_lo(w.w); f[7] = bf_hi(w.w); }
; __device__ __forceinline__ void ph_ret_fast(const Params& p, int jl, LAS unsigned char* lds, int tid, int lane, int wave) {
;     ...
;         for (int c = 0; c < 17; ++c) {
;             __syncthreads();
; #pragma unroll
;             for (int k_ = 0; k_ < 8; ++k_) { const int id_ = tid + 512 * k_, row_ = id_ >> 5, ch_ = id_ & 31; *(LAS v4u*)(lds + RT_K_OFF + row_ * RT_KP + ch_ * 16) = kst[k_]; }
; #pragma unroll
;             for (int k_ = 0; k_ < 2; ++k_) { const int id_ = tid + 512 * k_, row_ = id_ >> 3, ch_ = id_ & 7;
;                 float f[8]; unpack8(vst[k_], f); const float sc = exp2f(-(float)row_ * lg);
; #pragma unroll
;                 for (int e = 0; e < 8; ++e) f[e] *= sc;
;                 *(LAS v4u*)(lds + RT_V_OFF + row_ * RT_VP + ch_ * 16) = pack8(f); }
;             __syncthreads();
;             bf16x8 Pf[4];
;             { const int ii = i0 + fr; const float gi = exp2f((float)ii * lg);
; #pragma unroll
;               for (int s2 = 0; s2 < 4; ++s2) { f32x4 Dp[2];
;                   Dp[0] = (f32x4){0.f, 0.f, 0.f, 0.f}; Dp[1] = Dp[0];
;                   if (2 * s2 <= it_) {
;                       bf16x8 Ka[8], Kb[8];
; #pragma unroll
;                       for (int s = 0; s < 8; ++s) { Ka[s] = *(const LAS bf16x8*)(lds + RT_K_OFF + (16 * (2 * s2) + fr) * RT_KP + (32 * s + 8 * fq) * 2);
;                           Kb[s] = *(const LAS bf16x8*)(lds + RT_K_OFF + (16 * (2 * s2 + 1) + fr) * RT_KP + (32 * s + 8 * fq) * 2); }
;                       __builtin_amdgcn_sched_barrier(0);
;                       __builtin_amdgcn_s_setprio(1);
; #pragma unroll
;                       for (int s = 0; s < 8; ++s) { Dp[0] = __builtin_amdgcn_mfma_f32_16x16x32_bf16(Ka[s], Qf[s], Dp[0], 0, 0, 0); Dp[1] = __builtin_amdgcn_mfma_f32_16x16x32_bf16(Kb[s], Qf[s], Dp[1], 0, 0, 0); }
;                       __builtin_amdgcn_s_setprio(0);
;                       __builtin_amdgcn_sched_barrier(0);
;                   }
.LBB0_385:
	global_load_dwordx4 v[70:73], v[70:71], off offset:448
	s_cmpk_ge_i32 s27, 0x780
	s_cbranch_scc1 .Lpf_skip
	s_add_i32 s101, s94, s27
	s_addk_i32 s101, 0x90
	s_lshl_b32 s101, s101, 12
	v_and_b32_e32 v239, 3, v194
	v_lshlrev_b32_e32 v239, 7, v239
	v_lshl_or_b32 v239, v194, 10, v239
	v_and_b32_e32 v239, 0x7f180, v239
	v_add_u32_e32 v239, s101, v239
	global_load_dword v223, v239, s[86:87]
	global_load_dword v223, v239, s[90:91]
	s_nop 1
	v_and_b32_e32 v239, 3, v194
	v_lshlrev_b32_e32 v239, 5, v239
	v_lshl_or_b32 v239, v194, 10, v239
	v_and_b32_e32 v239, 0x7f060, v239
	v_add_u32_e32 v239, s101, v239
	global_load_dword v223, v239, s[88:89]
.Lpf_skip:
	s_addk_i32 s27, 0x80
	s_cmpk_eq_i32 s27, 0x800
	s_cbranch_scc1 .LBB0_439
.LBB0_386:
	s_waitcnt lgkmcnt(0)
	s_barrier
	s_waitcnt vmcnt(11)
	ds_write_b128 v186, v[2:5]
	ds_write_b128 v187, v[6:9]
	ds_write_b128 v188, v[10:13]
	ds_write_b128 v189, v[14:17]
	ds_write_b128 v190, v[18:21]
	ds_write_b128 v191, v[22:25]
	ds_write_b128 v192, v[26:29]
	ds_write_b128 v193, v[34:37]
	v_and_b32_e32 v2, 0xffff0000, v46
	v_lshlrev_b32_e32 v0, 16, v46
	v_lshlrev_b32_e32 v3, 16, v47
	v_and_b32_e32 v4, 0xffff0000, v47
	v_lshlrev_b32_e32 v5, 16, v48
	v_mul_f32_e32 v2, v205, v2
	v_and_b32_e32 v6, 0xffff0000, v48
	v_lshlrev_b32_e32 v7, 16, v49
	v_and_b32_e32 v8, 0xffff0000, v49
	v_mul_f32_e32 v0, v205, v0
	v_mul_f32_e32 v3, v205, v3
	v_mul_f32_e32 v4, v205, v4
	v_mul_f32_e32 v5, v205, v5
	v_cvt_pk_bf16_f32 v2, v0, v2
	v_mul_f32_e32 v6, v205, v6
	v_mul_f32_e32 v7, v205, v7
	v_mul_f32_e32 v8, v205, v8
	v_cvt_pk_bf16_f32 v3, v3, v4
	v_cvt_pk_bf16_f32 v4, v5, v6
	v_cvt_pk_bf16_f32 v5, v7, v8
	ds_write_b128 v195, v[2:5]
	v_lshlrev_b32_e32 v0, 16, v50
	v_and_b32_e32 v2, 0xffff0000, v50
	v_lshlrev_b32_e32 v3, 16, v51
	v_and_b32_e32 v4, 0xffff0000, v51
	v_lshlrev_b32_e32 v5, 16, v52
	v_and_b32_e32 v6, 0xffff0000, v52
	v_lshlrev_b32_e32 v7, 16, v53
	v_and_b32_e32 v8, 0xffff0000, v53
	v_mul_f32_e32 v0, v115, v0
	v_mul_f32_e32 v2, v115, v2
	v_mul_f32_e32 v3, v115, v3
	v_mul_f32_e32 v4, v115, v4
	v_mul_f32_e32 v5, v115, v5
	v_mul_f32_e32 v6, v115, v6
	v_mul_f32_e32 v7, v115, v7
	v_mul_f32_e32 v8, v115, v8
	v_cvt_pk_bf16_f32 v2, v0, v2
	v_cndmask_b32_e64 v0, 0, 1, s[4:5]
	v_cvt_pk_bf16_f32 v3, v3, v4
	v_cvt_pk_bf16_f32 v4, v5, v6
	v_cvt_pk_bf16_f32 v5, v7, v8
	v_cmp_ne_u32_e64 s[76:77], 1, v0
	s_andn2_b64 vcc, exec, s[4:5]
	v_mov_b32_e32 v6, 0
	v_mov_b32_e32 v7, 0
	v_mov_b32_e32 v8, 0
	v_mov_b32_e32 v9, 0
	v_mov_b32_e32 v10, 0
	v_mov_b32_e32 v11, 0
	v_mov_b32_e32 v12, 0
	v_mov_b32_e32 v13, 0
	ds_write_b128 v196, v[2:5]
	s_waitcnt lgkmcnt(0)
	s_barrier
	s_waitcnt vmcnt(3)
	s_cbranch_vccnz .LBB0_388
	ds_read_b128 v[2:5], v169
	ds_read_b128 v[6:9], v169 offset:64
	ds_read_b128 v[10:13], v169 offset:8448
	ds_read_b128 v[14:17], v169 offset:8512
	ds_read_b128 v[18:21], v169 offset:128
	ds_read_b128 v[22:25], v169 offset:192
	ds_read_b128 v[26:29], v169 offset:8576
	ds_read_b128 v[34:37], v169 offset:8640
	ds_read_b128 v[46:49], v169 offset:256
	ds_read_b128 v[50:53], v169 offset:320
	ds_read_b128 v[74:77], v169 offset:8704
	ds_read_b128 v[78:81], v169 offset:8768
	ds_read_b128 v[82:85], v169 offset:384
	ds_read_b128 v[86:89], v169 offset:448
	ds_read_b128 v[90:93], v169 offset:8832
	ds_read_b128 v[94:97], v169 offset:8896
	s_setprio 1
	s_waitcnt lgkmcnt(14)
	v_mfma_f32_16x16x32_bf16 v[2:5], v[2:5], v[30:33], 0
	s_waitcnt lgkmcnt(13)
	v_mfma_f32_16x16x32_bf16 v[10:13], v[10:13], v[30:33], 0
	v_mfma_f32_16x16x32_bf16 v[2:5], v[6:9], v[38:41], v[2:5]
	s_waitcnt lgkmcnt(12)
	v_mfma_f32_16x16x32_bf16 v[6:9], v[14:17], v[38:41], v[10:13]
	s_waitcnt lgkmcnt(11)
	v_mfma_f32_16x16x32_bf16 v[2:5], v[18:21], v[42:45], v[2:5]
	s_waitcnt lgkmcnt(9)
	v_mfma_f32_16x16x32_bf16 v[6:9], v[26:29], v[42:45], v[6:9]
	v_mfma_f32_16x16x32_bf16 v[2:5], v[22:25], v[54:57], v[2:5]
	s_waitcnt lgkmcnt(8)
	v_mfma_f32_16x16x32_bf16 v[6:9], v[34:37], v[54:57], v[6:9]
	s_waitcnt lgkmcnt(7)
	v_mfma_f32_16x16x32_bf16 v[2:5], v[46:49], v[58:61], v[2:5]
	s_waitcnt lgkmcnt(5)
	v_mfma_f32_16x16x32_bf16 v[6:9], v[74:77], v[58:61], v[6:9]
	v_mfma_f32_16x16x32_bf16 v[2:5], v[50:53], v[62:65], v[2:5]
	s_waitcnt lgkmcnt(4)
	v_mfma_f32_16x16x32_bf16 v[6:9], v[78:81], v[62:65], v[6:9]
	s_waitcnt lgkmcnt(3)
	v_mfma_f32_16x16x32_bf16 v[2:5], v[82:85], v[66:69], v[2:5]
	s_waitcnt lgkmcnt(1)
	v_mfma_f32_16x16x32_bf16 v[6:9], v[90:93], v[66:69], v[6:9]
	v_mfma_f32_16x16x32_bf16 v[10:13], v[86:89], v[70:73], v[2:5]
	s_waitcnt lgkmcnt(0)
	v_mfma_f32_16x16x32_bf16 v[6:9], v[94:97], v[70:73], v[6:9]
	s_setprio 0

; #define LAS __attribute__((address_space(3)))
; __device__ __forceinline__ void unpack8(const v4u w, float (&f)[8]) { f[0] = bf_lo(w.x); f[1] = bf_hi(w.x); f[2] = bf_lo(w.y); f[3] = bf_hi(w.y); f[4] = bf_lo(w.z); f[5] = bf_hi(w.z); f[6] = bf_lo(w.w); f[7] = bf_hi(w.w); }
; __device__ __forceinline__ void ph_ret_fast(const Params& p, int jl, LAS unsigned char* lds, int tid, int lane, int wave) {
;     ...
;         for (int c = 0; c < 17; ++c) {
;             __syncthreads();
; #pragma unroll
;             for (int k_ = 0; k_ < 8; ++k_) { const int id_ = tid + 512 * k_, row_ = id_ >> 5, ch_ = id_ & 31; *(LAS v4u*)(lds + RT_K_OFF + row_ * RT_KP + ch_ * 16) = kst[k_]; }
; #pragma unroll
;             for (int k_ = 0; k_ < 2; ++k_) { const int id_ = tid + 512 * k_, row_ = id_ >> 3, ch_ = id_ & 7;
;                 float f[8]; unpack8(vst[k_], f); const float sc = exp2f(-(float)row_ * lg);
; #pragma unroll
;                 for (int e = 0; e < 8; ++e) f[e] *= sc;
;                 *(LAS v4u*)(lds + RT_V_OFF + row_ * RT_VP + ch_ * 16) = pack8(f); }
;             __syncthreads();
;             bf16x8 Pf[4];
;             { const int ii = i0 + fr; const float gi = exp2f((float)ii * lg);
; #pragma unroll
;               for (int s2 = 0; s2 < 4; ++s2) { f32x4 Dp[2];
;                   Dp[0] = (f32x4){0.f, 0.f, 0.f, 0.f}; Dp[1] = Dp[0];
;                   if (2 * s2 <= it_) {
;                       bf16x8 Ka[8], Kb[8];
; #pragma unroll
;                       for (int s = 0; s < 8; ++s) { Ka[s] = *(const LAS bf16x8*)(lds + RT_K_OFF + (16 * (2 * s2) + fr) * RT_KP + (32 * s + 8 * fq) * 2);
;                           Kb[s] = *(const LAS bf16x8*)(lds + RT_K_OFF + (16 * (2 * s2 + 1) + fr) * RT_KP + (32 * s + 8 * fq) * 2); }
;                       __builtin_amdgcn_sched_barrier(0);
;                       __builtin_amdgcn_s_setprio(1);
; #pragma unroll
;                       for (int s = 0; s < 8; ++s) { Dp[0] = __builtin_amdgcn_mfma_f32_16x16x32_bf16(Ka[s], Qf[s], Dp[0], 0, 0, 0); Dp[1] = __builtin_amdgcn_mfma_f32_16x16x32_bf16(Kb[s], Qf[s], Dp[1], 0, 0, 0); }
;                       __builtin_amdgcn_s_setprio(0);
;                       __builtin_amdgcn_sched_barrier(0);
;                   }
.LBB0_438:
	v_mov_b32_e32 v70, 0
	v_mov_b32_e32 v71, v70
	v_mov_b32_e32 v72, v70
	v_mov_b32_e32 v73, v70
	s_waitcnt vmcnt(0)
	s_addk_i32 s27, 0x80
	s_cmpk_eq_i32 s27, 0x800
	s_cbranch_scc0 .LBB0_386
.LBB0_439:
	s_waitcnt lgkmcnt(0)
	s_barrier
	s_waitcnt vmcnt(8)
	ds_write_b128 v186, v[2:5]
	ds_write_b128 v187, v[6:9]
	ds_write_b128 v188, v[10:13]
	ds_write_b128 v189, v[14:17]
	ds_write_b128 v190, v[18:21]
	ds_write_b128 v191, v[22:25]
	ds_write_b128 v192, v[26:29]
	ds_write_b128 v193, v[34:37]
	v_lshlrev_b32_e32 v2, 16, v46
	v_and_b32_e32 v3, 0xffff0000, v46
	v_lshlrev_b32_e32 v4, 16, v47
	v_and_b32_e32 v5, 0xffff0000, v47
	v_lshlrev_b32_e32 v6, 16, v48
	v_and_b32_e32 v7, 0xffff0000, v48
	v_lshlrev_b32_e32 v8, 16, v49
	v_and_b32_e32 v9, 0xffff0000, v49
	v_mul_f32_e32 v2, v205, v2
	v_mul_f32_e32 v3, v205, v3
	v_mul_f32_e32 v4, v205, v4
	v_mul_f32_e32 v5, v205, v5
	v_mul_f32_e32 v6, v205, v6
	v_mul_f32_e32 v7, v205, v7
	v_mul_f32_e32 v8, v205, v8
	v_mul_f32_e32 v9, v205, v9
	v_cvt_pk_bf16_f32 v2, v2, v3
	v_cvt_pk_bf16_f32 v3, v4, v5
	v_cvt_pk_bf16_f32 v4, v6, v7
	v_cvt_pk_bf16_f32 v5, v8, v9
	ds_write_b128 v195, v[2:5]
	v_lshlrev_b32_e32 v2, 16, v50
	v_and_b32_e32 v3, 0xffff0000, v50
	v_lshlrev_b32_e32 v4, 16, v51
	v_and_b32_e32 v5, 0xffff0000, v51
	v_lshlrev_b32_e32 v6, 16, v52
	v_and_b32_e32 v7, 0xffff0000, v52
	v_lshlrev_b32_e32 v8, 16, v53
	v_and_b32_e32 v9, 0xffff0000, v53
	v_mul_f32_e32 v2, v115, v2
	v_mul_f32_e32 v3, v115, v3
	v_mul_f32_e32 v4, v115, v4
	v_mul_f32_e32 v5, v115, v5
	v_mul_f32_e32 v6, v115, v6
	v_mul_f32_e32 v7, v115, v7
	v_mul_f32_e32 v8, v115, v8
	v_mul_f32_e32 v9, v115, v9
	v_cvt_pk_bf16_f32 v2, v2, v3
	v_cvt_pk_bf16_f32 v3, v4, v5
	v_cvt_pk_bf16_f32 v4, v6, v7
	v_cvt_pk_bf16_f32 v5, v8, v9
	ds_write_b128 v196, v[2:5]
	v_mov_b32_e32 v6, 0
	s_and_b64 vcc, exec, s[76:77]
	v_mov_b32_e32 v2, 0
	v_mov_b32_e32 v3, 0
	v_mov_b32_e32 v4, 0
	v_mov_b32_e32 v5, 0
	v_mov_b32_e32 v8, 0
	v_mov_b32_e32 v9, 0
	v_mov_b32_e32 v10, 0
	v_mov_b32_e32 v11, 0
	s_waitcnt lgkmcnt(0)
	s_barrier
	s_waitcnt vmcnt(0)
	v_mov_b32_e32 v223, 0x7fc00000
	s_cbranch_vccnz .LBB0_441
	ds_read_b128 v[2:5], v169
	ds_read_b128 v[8:11], v169 offset:64
	ds_read_b128 v[12:15], v169 offset:8448
	ds_read_b128 v[16:19], v169 offset:8512
	ds_read_b128 v[20:23], v169 offset:128
	ds_read_b128 v[24:27], v169 offset:192
	ds_read_b128 v[34:37], v169 offset:8576
	ds_read_b128 v[46:49], v169 offset:8640
	ds_read_b128 v[50:53], v169 offset:256
	ds_read_b128 v[78:81], v169 offset:320
	ds_read_b128 v[82:85], v169 offset:8704
	ds_read_b128 v[86:89], v169 offset:8768
	ds_read_b128 v[90:93], v169 offset:384
	ds_read_b128 v[94:97], v169 offset:448
	ds_read_b128 v[206:209], v169 offset:8832
	ds_read_b128 v[210:213], v169 offset:8896
	s_setprio 1
	s_waitcnt lgkmcnt(14)
	v_mfma_f32_16x16x32_bf16 v[2:5], v[2:5], v[30:33], 0
	s_waitcnt lgkmcnt(13)
	v_mfma_f32_16x16x32_bf16 v[12:15], v[12:15], v[30:33], 0
	v_mfma_f32_16x16x32_bf16 v[2:5], v[8:11], v[38:41], v[2:5]
	s_waitcnt lgkmcnt(12)
	v_mfma_f32_16x16x32_bf16 v[8:11], v[16:19], v[38:41], v[12:15]
	s_waitcnt lgkmcnt(11)
	v_mfma_f32_16x16x32_bf16 v[2:5], v[20:23], v[42:45], v[2:5]
	s_waitcnt lgkmcnt(9)
	v_mfma_f32_16x16x32_bf16 v[8:11], v[34:37], v[42:45], v[8:11]
	v_mfma_f32_16x16x32_bf16 v[2:5], v[24:27], v[54:57], v[2:5]
	s_waitcnt lgkmcnt(8)
	v_mfma_f32_16x16x32_bf16 v[8:11], v[46:49], v[54:57], v[8:11]
	s_waitcnt lgkmcnt(7)
	v_mfma_f32_16x16x32_bf16 v[2:5], v[50:53], v[58:61], v[2:5]
	s_waitcnt lgkmcnt(5)
	v_mfma_f32_16x16x32_bf16 v[8:11], v[82:85], v[58:61], v[8:11]
	v_mfma_f32_16x16x32_bf16 v[2:5], v[78:81], v[62:65], v[2:5]
	s_waitcnt lgkmcnt(4)
	v_mfma_f32_16x16x32_bf16 v[8:11], v[86:89], v[62:65], v[8:11]
	s_waitcnt lgkmcnt(3)
	v_mfma_f32_16x16x32_bf16 v[2:5], v[90:93], v[66:69], v[2:5]
	s_waitcnt lgkmcnt(1)
	v_mfma_f32_16x16x32_bf16 v[12:15], v[206:209], v[66:69], v[8:11]
	v_mfma_f32_16x16x32_bf16 v[8:11], v[94:97], v[70:73], v[2:5]
	s_waitcnt lgkmcnt(0)
	v_mfma_f32_16x16x32_bf16 v[2:5], v[210:213], v[70:73], v[12:15]
	s_setprio 0
